# v142 + dead global-address arithmetic of the former SSD-conv weight loads removed (32 VALU per iteration)
# speedup vs baseline: 1.0035x; 1.0011x over previous
.LBB0_224:
	s_or_b64 exec, exec, s[4:5]
	v_lshlrev_b64 v[52:53], 2, v[52:53]
	v_add_u32_e32 v233, 0x8000, v52
	ds_read_b128 v[114:117], v233 offset:49168
	ds_read_b128 v[122:125], v233 offset:49152
	ds_read_b128 v[126:129], v233 offset:16
	ds_read_b128 v[130:133], v233
	s_mov_b64 s[38:39], 0x3000
	ds_read_b128 v[134:137], v233 offset:12288
	s_nop 0
	ds_read_b128 v[138:141], v233 offset:12304
	s_movk_i32 s4, 0x6000
	s_mov_b64 s[40:41], 0x6000
	s_mov_b64 s[48:49], 0x9000
	s_mov_b32 s5, 0x9000
	s_cmp_lt_i32 s20, 40
	s_waitcnt lgkmcnt(2)
	v_mov_b32_e32 v118, v130
	s_waitcnt lgkmcnt(1)
	v_mov_b32_e32 v119, v134
	v_pk_mul_f32 v[38:39], v[118:119], v[38:39]
	v_mov_b32_e32 v134, v131
	v_add_f32_e32 v0, v122, v38
	v_add_f32_e32 v0, v0, v39
	s_waitcnt lgkmcnt(0)
	v_mov_b32_e32 v38, v138
	v_mov_b32_e32 v39, v126
	v_mov_b32_e32 v126, v139
	v_pk_mul_f32 v[38:39], v[38:39], v[102:103]
	v_pk_mul_f32 v[10:11], v[126:127], v[10:11]
	v_add_f32_e32 v39, v39, v114
	v_add_f32_e32 v11, v11, v115
	v_add_f32_e32 v118, v38, v39
	v_pk_mul_f32 v[38:39], v[134:135], v[106:107]
	v_add_f32_e32 v107, v10, v11
	v_mov_b32_e32 v10, v132
	v_mov_b32_e32 v11, v136
	v_pk_mul_f32 v[10:11], v[10:11], v[40:41]
	v_mov_b32_e32 v136, v133
	v_add_f32_e32 v10, v124, v10
	v_add_f32_e32 v119, v10, v11
	v_mov_b32_e32 v10, v140
	v_mov_b32_e32 v11, v128
	v_pk_mul_f32 v[10:11], v[10:11], v[98:99]
	v_mov_b32_e32 v128, v141
	v_add_f32_e32 v11, v11, v116
	v_add_f32_e32 v122, v10, v11
	v_pk_mul_f32 v[10:11], v[136:137], v[100:101]
	v_add_f32_e32 v38, v123, v38
	v_add_f32_e32 v10, v125, v10
	v_add_f32_e32 v123, v10, v11
	v_pk_mul_f32 v[10:11], v[128:129], v[12:13]
	v_add_f32_e32 v106, v38, v39
	v_add_f32_e32 v11, v11, v117
	v_add_f32_e32 v124, v10, v11
	s_nop 0
	ds_read_b128 v[10:13], v233 offset:24576
	s_nop 0
	ds_read_b128 v[38:41], v233 offset:24592
	ds_read_b128 v[98:101], v233 offset:36864
	ds_read_b128 v[114:117], v233 offset:36880
	s_waitcnt lgkmcnt(3)
	v_mov_b32_e32 v52, v10
	s_waitcnt lgkmcnt(1)
	v_mov_b32_e32 v53, v98
	v_pk_mul_f32 v[46:47], v[52:53], v[46:47]
	v_mov_b32_e32 v98, v11
	v_add_f32_e32 v0, v0, v46
	v_add_f32_e32 v0, v0, v47
	s_waitcnt lgkmcnt(0)
	v_mov_b32_e32 v46, v114
	v_mov_b32_e32 v47, v38
	v_pk_mul_f32 v[46:47], v[46:47], v[110:111]
	v_mov_b32_e32 v38, v115
	v_add_f32_e32 v10, v47, v118
	v_add_f32_e32 v46, v46, v10
	v_pk_mul_f32 v[10:11], v[98:99], v[112:113]
	s_nop 0
	v_add_f32_e32 v10, v106, v10
	v_add_f32_e32 v47, v10, v11
	v_pk_mul_f32 v[10:11], v[38:39], v[42:43]
	s_nop 0
	v_add_f32_e32 v11, v11, v107
	v_add_f32_e32 v38, v10, v11
	v_mov_b32_e32 v10, v12
	v_mov_b32_e32 v11, v100
	v_pk_mul_f32 v[10:11], v[10:11], v[48:49]
	v_mov_b32_e32 v100, v13
	v_add_f32_e32 v10, v119, v10
	v_add_f32_e32 v12, v10, v11
	v_mov_b32_e32 v10, v116
	v_mov_b32_e32 v11, v40
	v_pk_mul_f32 v[10:11], v[10:11], v[104:105]
	v_mov_b32_e32 v40, v117
	v_add_f32_e32 v11, v11, v122
	v_add_f32_e32 v39, v10, v11
	v_pk_mul_f32 v[10:11], v[100:101], v[108:109]
	s_nop 0
	v_add_f32_e32 v10, v123, v10
	v_add_f32_e32 v13, v10, v11
	v_pk_mul_f32 v[10:11], v[40:41], v[44:45]
	v_mul_f32_e32 v40, 0xbfb8aa3b, v12
	v_exp_f32_e32 v40, v40
	v_mul_f32_e32 v41, 0xbfb8aa3b, v38
	v_exp_f32_e32 v41, v41
	v_add_f32_e32 v11, v11, v124
	v_add_f32_e32 v40, 1.0, v40
	v_rcp_f32_e32 v40, v40
	v_add_f32_e32 v41, 1.0, v41
	v_rcp_f32_e32 v41, v41
	v_add_f32_e32 v10, v10, v11
	v_mul_f32_e32 v11, 0xbfb8aa3b, v0
	v_mul_f32_e32 v12, v12, v40
	v_mul_f32_e32 v40, 0xbfb8aa3b, v13
	v_exp_f32_e32 v11, v11
	v_exp_f32_e32 v40, v40
	v_mul_f32_e32 v38, v38, v41
	v_mul_f32_e32 v41, 0xbfb8aa3b, v39
	v_exp_f32_e32 v41, v41
	v_add_f32_e32 v11, 1.0, v11
	v_add_f32_e32 v40, 1.0, v40
	v_rcp_f32_e32 v11, v11
	v_rcp_f32_e32 v40, v40
	v_add_f32_e32 v41, 1.0, v41
	v_rcp_f32_e32 v41, v41
	v_mul_f32_e32 v0, v0, v11
	v_mul_f32_e32 v11, 0xbfb8aa3b, v47
	v_mul_f32_e32 v13, v13, v40
	v_mul_f32_e32 v40, 0xbfb8aa3b, v46
	v_exp_f32_e32 v11, v11
	v_exp_f32_e32 v40, v40
	v_mul_f32_e32 v39, v39, v41
	v_mul_f32_e32 v41, 0xbfb8aa3b, v10
	v_exp_f32_e32 v41, v41
	v_add_f32_e32 v11, 1.0, v11
	v_add_f32_e32 v40, 1.0, v40
	v_rcp_f32_e32 v11, v11
	v_rcp_f32_e32 v40, v40
	v_add_f32_e32 v41, 1.0, v41
	v_rcp_f32_e32 v41, v41
	v_mul_f32_e32 v11, v47, v11
	v_mul_f32_e32 v40, v46, v40
	v_lshlrev_b64 v[46:47], 2, v[50:51]
	v_add_u32_e32 v233, 0x8000, v46
	v_lshl_add_u64 v[98:99], s[8:9], 0, v[46:47]
	v_mul_f32_e32 v41, v10, v41
	v_cvt_pk_bf16_f32 v10, v0, v11
	v_cvt_pk_bf16_f32 v11, v12, v13
	v_cvt_pk_bf16_f32 v12, v40, v38
	v_cvt_pk_bf16_f32 v13, v39, v41
	ds_read_b128 v[38:41], v233 offset:49168
	s_nop 0
	ds_read_b128 v[42:45], v233 offset:49152
	s_nop 0
	ds_read_b128 v[46:49], v233 offset:16
	ds_read_b128 v[50:53], v233
	ds_read_b128 v[102:105], v233 offset:12288
	s_nop 0
	ds_read_b128 v[106:109], v233 offset:12304
	s_waitcnt lgkmcnt(2)
	v_mov_b32_e32 v100, v50
	s_waitcnt lgkmcnt(1)
	v_mov_b32_e32 v101, v102
	v_pk_mul_f32 v[34:35], v[100:101], v[34:35]
	v_mov_b32_e32 v102, v51
	v_add_f32_e32 v0, v42, v34
	v_add_f32_e32 v100, v0, v35
	s_waitcnt lgkmcnt(0)
	v_mov_b32_e32 v34, v106
	v_mov_b32_e32 v35, v46
	v_pk_mul_f32 v[34:35], v[34:35], v[94:95]
	v_mov_b32_e32 v46, v107
	v_add_f32_e32 v0, v35, v38
	v_add_f32_e32 v94, v34, v0
	v_pk_mul_f32 v[34:35], v[102:103], v[96:97]
	v_pk_mul_f32 v[30:31], v[46:47], v[30:31]
	v_add_f32_e32 v0, v43, v34
	v_add_f32_e32 v51, v0, v35
	v_add_f32_e32 v0, v31, v39
	v_add_f32_e32 v50, v30, v0
	v_mov_b32_e32 v30, v52
	v_mov_b32_e32 v31, v104
	v_pk_mul_f32 v[30:31], v[30:31], v[36:37]
	v_mov_b32_e32 v104, v53
	v_add_f32_e32 v0, v44, v30
	v_add_f32_e32 v0, v0, v31
	v_mov_b32_e32 v30, v108
	v_mov_b32_e32 v31, v48
	v_pk_mul_f32 v[30:31], v[30:31], v[90:91]
	v_mov_b32_e32 v48, v109
	v_add_f32_e32 v31, v31, v40
	v_add_f32_e32 v46, v30, v31
	v_pk_mul_f32 v[30:31], v[104:105], v[92:93]
	v_add_f32_e32 v30, v45, v30
	v_add_f32_e32 v47, v30, v31
	v_pk_mul_f32 v[30:31], v[48:49], v[32:33]
	v_add_f32_e32 v31, v31, v41
	s_nop 0
	v_add_f32_e32 v48, v30, v31
	ds_read_b128 v[34:37], v233 offset:24576
	s_nop 0
	ds_read_b128 v[30:33], v233 offset:24592
	s_nop 0
	ds_read_b128 v[38:41], v233 offset:36864
	s_nop 0
	ds_read_b128 v[42:45], v233 offset:36880
	s_waitcnt lgkmcnt(3)
	v_mov_b32_e32 v52, v34
	s_waitcnt lgkmcnt(1)
	v_mov_b32_e32 v53, v38
	v_pk_mul_f32 v[26:27], v[52:53], v[26:27]
	v_mov_b32_e32 v38, v35
	v_add_f32_e32 v26, v100, v26
	v_add_f32_e32 v34, v26, v27
	s_waitcnt lgkmcnt(0)
	v_mov_b32_e32 v26, v42
	v_mov_b32_e32 v27, v30
	v_pk_mul_f32 v[26:27], v[26:27], v[88:89]
	v_mov_b32_e32 v30, v43
	v_add_f32_e32 v27, v27, v94
	v_add_f32_e32 v42, v26, v27
	v_pk_mul_f32 v[26:27], v[38:39], v[86:87]
	v_pk_mul_f32 v[22:23], v[30:31], v[22:23]
	v_add_f32_e32 v26, v51, v26
	v_add_f32_e32 v23, v23, v50
	v_add_f32_e32 v26, v26, v27
	v_add_f32_e32 v27, v22, v23
	v_mov_b32_e32 v22, v36
	v_mov_b32_e32 v23, v40
	v_pk_mul_f32 v[22:23], v[22:23], v[28:29]
	v_mov_b32_e32 v40, v37
	v_add_f32_e32 v0, v0, v22
	v_add_f32_e32 v0, v0, v23
	v_mov_b32_e32 v22, v44
	v_mov_b32_e32 v23, v32
	v_pk_mul_f32 v[22:23], v[22:23], v[82:83]
	v_mov_b32_e32 v32, v45
	v_add_f32_e32 v23, v23, v46
	v_add_f32_e32 v28, v22, v23
	v_pk_mul_f32 v[22:23], v[40:41], v[84:85]
	s_nop 0
	v_add_f32_e32 v22, v47, v22
	v_add_f32_e32 v29, v22, v23
	v_pk_mul_f32 v[22:23], v[32:33], v[24:25]
	v_mul_f32_e32 v25, 0xbfb8aa3b, v0
	v_exp_f32_e32 v25, v25
	v_mul_f32_e32 v24, 0xbfb8aa3b, v26
	v_exp_f32_e32 v24, v24
	v_add_f32_e32 v23, v23, v48
	v_add_f32_e32 v25, 1.0, v25
	v_rcp_f32_e32 v25, v25
	v_add_f32_e32 v24, 1.0, v24
	v_rcp_f32_e32 v24, v24
	v_add_f32_e32 v22, v22, v23
	v_mul_f32_e32 v0, v0, v25
	v_mul_f32_e32 v25, 0xbfb8aa3b, v29
	v_exp_f32_e32 v25, v25
	v_mul_f32_e32 v24, v26, v24
	v_mul_f32_e32 v26, 0xbfb8aa3b, v42
	v_mul_f32_e32 v23, 0xbfb8aa3b, v34
	v_add_f32_e32 v25, 1.0, v25
	v_rcp_f32_e32 v25, v25
	v_exp_f32_e32 v26, v26
	v_exp_f32_e32 v23, v23
	v_mul_f32_e32 v25, v29, v25
	v_mul_f32_e32 v29, 0xbfb8aa3b, v27
	v_exp_f32_e32 v29, v29
	v_add_f32_e32 v26, 1.0, v26
	v_add_f32_e32 v23, 1.0, v23
	v_rcp_f32_e32 v26, v26
	v_add_f32_e32 v29, 1.0, v29
	v_rcp_f32_e32 v29, v29
	v_rcp_f32_e32 v23, v23
	v_mul_f32_e32 v26, v42, v26
	v_mul_f32_e32 v27, v27, v29
	v_mul_f32_e32 v29, 0xbfb8aa3b, v28
	v_exp_f32_e32 v29, v29
	v_mul_f32_e32 v23, v34, v23
	v_add_f32_e32 v29, 1.0, v29
	v_rcp_f32_e32 v29, v29
	s_nop 0
	v_mul_f32_e32 v28, v28, v29
	v_mul_f32_e32 v29, 0xbfb8aa3b, v22
	v_exp_f32_e32 v29, v29
	s_nop 0
	v_add_f32_e32 v29, 1.0, v29
	v_rcp_f32_e32 v29, v29
	s_nop 0
	v_mul_f32_e32 v29, v22, v29
	v_cvt_pk_bf16_f32 v22, v23, v24
	v_cvt_pk_bf16_f32 v24, v26, v27
	v_lshlrev_b64 v[26:27], 2, v[76:77]
	v_add_u32_e32 v233, 0x8000, v26
	v_cvt_pk_bf16_f32 v23, v0, v25
	v_cvt_pk_bf16_f32 v25, v28, v29
	ds_read_b128 v[28:31], v233 offset:49168
	ds_read_b128 v[40:43], v233 offset:49152
	ds_read_b128 v[44:47], v233 offset:16
	ds_read_b128 v[48:51], v233
	ds_read_b128 v[82:85], v233 offset:12288
	ds_read_b128 v[86:89], v233 offset:12304
	s_waitcnt lgkmcnt(2)
	v_mov_b32_e32 v32, v48
	s_waitcnt lgkmcnt(1)
	v_mov_b32_e32 v33, v82
	v_pk_mul_f32 v[18:19], v[32:33], v[18:19]
	v_mov_b32_e32 v82, v49
	v_add_f32_e32 v0, v40, v18
	v_add_f32_e32 v40, v0, v19
	s_waitcnt lgkmcnt(0)
	v_mov_b32_e32 v18, v86
	v_mov_b32_e32 v19, v44
	v_pk_mul_f32 v[18:19], v[18:19], v[78:79]
	v_mov_b32_e32 v44, v87
	v_add_f32_e32 v0, v19, v28
	v_add_f32_e32 v39, v18, v0
	v_pk_mul_f32 v[18:19], v[82:83], v[80:81]
	v_pk_mul_f32 v[14:15], v[44:45], v[14:15]
	v_add_f32_e32 v0, v41, v18
	v_add_f32_e32 v38, v0, v19
	v_add_f32_e32 v0, v15, v29
	v_add_f32_e32 v37, v14, v0
	v_mov_b32_e32 v14, v50
	v_mov_b32_e32 v15, v84
	v_pk_mul_f32 v[14:15], v[14:15], v[20:21]
	v_mov_b32_e32 v84, v51
	v_add_f32_e32 v0, v42, v14
	v_add_f32_e32 v36, v0, v15
	v_mov_b32_e32 v14, v88
	v_mov_b32_e32 v15, v46
	v_pk_mul_f32 v[14:15], v[14:15], v[72:73]
	v_mov_b32_e32 v46, v89
	v_add_f32_e32 v0, v15, v30
	v_add_f32_e32 v35, v14, v0
	v_pk_mul_f32 v[14:15], v[84:85], v[74:75]
	s_nop 0
	v_add_f32_e32 v0, v43, v14
	v_add_f32_e32 v34, v0, v15
	v_pk_mul_f32 v[14:15], v[46:47], v[16:17]
	v_add_f32_e32 v0, v15, v31
	s_nop 0
	v_add_f32_e32 v0, v14, v0
	ds_read_b128 v[18:21], v233 offset:24576
	s_nop 0
	ds_read_b128 v[14:17], v233 offset:24592
	ds_read_b128 v[26:29], v233 offset:36864
	s_nop 0
	ds_read_b128 v[30:33], v233 offset:36880
	s_barrier
	s_waitcnt lgkmcnt(3)
	v_mov_b32_e32 v42, v18
	s_waitcnt lgkmcnt(1)
	v_mov_b32_e32 v43, v26
	v_pk_mul_f32 v[6:7], v[42:43], v[6:7]
	v_mov_b32_e32 v26, v19
	v_add_f32_e32 v6, v40, v6
	v_add_f32_e32 v18, v6, v7
	s_waitcnt lgkmcnt(0)
	v_mov_b32_e32 v6, v30
	v_mov_b32_e32 v7, v14
	v_pk_mul_f32 v[6:7], v[6:7], v[70:71]
	v_mov_b32_e32 v14, v31
	v_add_f32_e32 v7, v7, v39
	v_add_f32_e32 v30, v6, v7
	v_pk_mul_f32 v[6:7], v[26:27], v[68:69]
	v_pk_mul_f32 v[2:3], v[14:15], v[2:3]
	v_add_f32_e32 v6, v38, v6
	v_add_f32_e32 v3, v3, v37
	v_add_f32_e32 v6, v6, v7
	v_add_f32_e32 v7, v2, v3
	v_mov_b32_e32 v2, v20
	v_mov_b32_e32 v3, v28
	v_pk_mul_f32 v[2:3], v[2:3], v[8:9]
	v_mov_b32_e32 v28, v21
	v_add_f32_e32 v2, v36, v2
	v_add_f32_e32 v8, v2, v3
	v_mov_b32_e32 v2, v32
	v_mov_b32_e32 v3, v16
	v_pk_mul_f32 v[2:3], v[2:3], v[66:67]
	v_mov_b32_e32 v16, v33
	v_add_f32_e32 v3, v3, v35
	v_add_f32_e32 v9, v2, v3
	v_pk_mul_f32 v[2:3], v[28:29], v[64:65]
	s_nop 0
	v_add_f32_e32 v2, v34, v2
	v_add_f32_e32 v14, v2, v3
	v_pk_mul_f32 v[2:3], v[16:17], v[4:5]
	v_mul_f32_e32 v4, 0xbfb8aa3b, v8
	v_exp_f32_e32 v4, v4
	v_add_f32_e32 v0, v3, v0
	v_mul_f32_e32 v3, 0xbfb8aa3b, v6
	v_exp_f32_e32 v3, v3
	v_add_f32_e32 v4, 1.0, v4
	v_rcp_f32_e32 v4, v4
	v_add_f32_e32 v0, v2, v0
	v_add_f32_e32 v3, 1.0, v3
	v_rcp_f32_e32 v3, v3
	v_mul_f32_e32 v4, v8, v4
	v_mul_f32_e32 v8, 0xbfb8aa3b, v7
	v_exp_f32_e32 v8, v8
	v_mul_f32_e32 v2, 0xbfb8aa3b, v18
	v_mul_f32_e32 v3, v6, v3
	v_mul_f32_e32 v6, 0xbfb8aa3b, v30
	v_add_f32_e32 v8, 1.0, v8
	v_rcp_f32_e32 v8, v8
	v_exp_f32_e32 v2, v2
	v_mul_f32_e32 v5, 0xbfb8aa3b, v14
	v_exp_f32_e32 v6, v6
	v_mul_f32_e32 v7, v7, v8
	v_mul_f32_e32 v8, 0xbfb8aa3b, v9
	v_exp_f32_e32 v8, v8
	v_exp_f32_e32 v5, v5
	v_add_f32_e32 v2, 1.0, v2
	v_add_f32_e32 v6, 1.0, v6
	v_add_f32_e32 v8, 1.0, v8
	v_rcp_f32_e32 v8, v8
	v_rcp_f32_e32 v2, v2
	v_add_f32_e32 v5, 1.0, v5
	v_rcp_f32_e32 v6, v6
	v_mul_f32_e32 v8, v9, v8
	v_mul_f32_e32 v9, 0xbfb8aa3b, v0
	v_exp_f32_e32 v9, v9
	v_rcp_f32_e32 v5, v5
	v_mul_f32_e32 v2, v18, v2
	v_mul_f32_e32 v6, v30, v6
	v_add_f32_e32 v9, 1.0, v9
	v_rcp_f32_e32 v9, v9
	v_mul_f32_e32 v5, v14, v5
	v_cvt_pk_bf16_f32 v2, v2, v3
	v_cvt_pk_bf16_f32 v3, v4, v5
	v_mul_f32_e32 v0, v0, v9
	v_cvt_pk_bf16_f32 v4, v6, v7
	v_add_u32_e32 v6, s19, v54
	v_cvt_pk_bf16_f32 v5, v8, v0
	v_ashrrev_i32_e32 v7, 31, v6
	v_lshlrev_b32_e32 v0, 1, v56
	s_cbranch_scc1 .LBB0_226
	v_lshlrev_b64 v[8:9], 10, v[6:7]
	v_lshl_add_u64 v[8:9], s[14:15], 0, v[8:9]
	s_add_i32 s88, s22, 0xfffff600
	v_lshl_add_u64 v[8:9], s[88:89], 1, v[8:9]
	v_lshl_add_u64 v[8:9], v[8:9], 0, v[0:1]
	global_store_dwordx4 v[8:9], v[10:13], off
